# E43: E42 + the XCD leaders no longer republish the per-XCD generation (nobody polls it any more), so a leader starts the next phase without waiting for that atomic
# speedup vs baseline: 1.0116x; 1.0024x over previous
; DI unsigned xb_ld(unsigned* p)              { return __hip_atomic_load(p, __ATOMIC_RELAXED, __HIP_MEMORY_SCOPE_AGENT); }
; DI unsigned xb_add(unsigned* p, unsigned v) { return __hip_atomic_fetch_add(p, v, __ATOMIC_RELAXED, __HIP_MEMORY_SCOPE_AGENT); }
; #define XB_SPIN(cond, bar) do { unsigned _sp = 0; while (cond) { __builtin_amdgcn_s_sleep(1); \
;     if ((++_sp & 255u) == 0u) { if (xb_ld(&(bar)[XB_TMO])) break; if (_sp > XB_SPIN_CAP) { atomicAdd(&(bar)[XB_TMO], 1u); break; } } } } while (0)
; DI void xcd_barrier(const XcdBarrier& b) {
;     ...
;             else XB_SPIN(xb_ld(&bar[XB_TOPGEN]) == tg, bar);
;             __builtin_amdgcn_fence(__ATOMIC_ACQUIRE, "agent");
;             xb_add(&bar[XB_XGEN(b.x)], 1u);
;             asm volatile("s_waitcnt vmcnt(0)" ::: "memory");
.LBB0_89:
	s_or_b64 exec, exec, s[6:7]
	v_mov_b32_e32 v0, 0
	v_mov_b32_e32 v1, 1
	s_waitcnt vmcnt(0)
	buffer_inv sc1
	s_waitcnt vmcnt(0)

; DI unsigned xb_ld(unsigned* p)              { return __hip_atomic_load(p, __ATOMIC_RELAXED, __HIP_MEMORY_SCOPE_AGENT); }
; DI unsigned xb_add(unsigned* p, unsigned v) { return __hip_atomic_fetch_add(p, v, __ATOMIC_RELAXED, __HIP_MEMORY_SCOPE_AGENT); }
; #define XB_SPIN(cond, bar) do { unsigned _sp = 0; while (cond) { __builtin_amdgcn_s_sleep(1); \
;     if ((++_sp & 255u) == 0u) { if (xb_ld(&(bar)[XB_TMO])) break; if (_sp > XB_SPIN_CAP) { atomicAdd(&(bar)[XB_TMO], 1u); break; } } } } while (0)
; DI void xcd_barrier(const XcdBarrier& b) {
;     ...
;             else XB_SPIN(xb_ld(&bar[XB_TOPGEN]) == tg, bar);
;             __builtin_amdgcn_fence(__ATOMIC_ACQUIRE, "agent");
;             xb_add(&bar[XB_XGEN(b.x)], 1u);
;             asm volatile("s_waitcnt vmcnt(0)" ::: "memory");
.LBB0_764:
	s_or_b64 exec, exec, s[4:5]
	v_readlane_b32 s4, v253, 54
	v_readlane_b32 s5, v253, 55
	s_waitcnt vmcnt(0)
	buffer_inv sc1
	s_nop 2
	s_waitcnt vmcnt(0)
